# G1 (256x128-tile) K-loop: LDS fragment reads for the next 16-deep K-step issued before the current MFMAs (register double buffer)
# speedup vs baseline: 1.0070x; 1.0021x over previous
.LBB0_1685:
	s_or_b64 exec, exec, s[6:7]
	s_add_i32 s6, s13, 0
	v_add_u32_e32 v120, s6, v109
	v_add_u32_e32 v119, s6, v110
	v_add_u32_e32 v121, v120, v112
	ds_read_b128 v[122:125], v121
	ds_read_b128 v[130:133], v121 offset:4096
	ds_read_b128 v[134:137], v121 offset:8192
	ds_read_b128 v[138:141], v121 offset:12288
	v_add_u32_e32 v121, v119, v112
	ds_read_b128 v[142:145], v121 offset:32768
	v_add_u32_e32 v121, v120, v111
	ds_read_b128 v[146:149], v121
	ds_read_b128 v[150:153], v121 offset:4096
	ds_read_b128 v[154:157], v121 offset:8192
	ds_read_b128 v[158:161], v121 offset:12288
	v_add_u32_e32 v121, v119, v111
	ds_read_b128 v[162:165], v121 offset:32768
	s_setprio 1
	s_waitcnt lgkmcnt(5)
	v_mfma_f32_32x32x16_bf16 v[48:63], v[122:125], v[142:145], v[48:63]
	v_mfma_f32_32x32x16_bf16 v[32:47], v[130:133], v[142:145], v[32:47]
	v_mfma_f32_32x32x16_bf16 v[16:31], v[134:137], v[142:145], v[16:31]
	v_mfma_f32_32x32x16_bf16 v[0:15], v[138:141], v[142:145], v[0:15]
	s_setprio 0
	v_add_u32_e32 v121, v120, v100
	ds_read_b128 v[122:125], v121
	ds_read_b128 v[130:133], v121 offset:4096
	ds_read_b128 v[134:137], v121 offset:8192
	ds_read_b128 v[138:141], v121 offset:12288
	v_add_u32_e32 v121, v119, v100
	ds_read_b128 v[142:145], v121 offset:32768
	s_setprio 1
	s_waitcnt lgkmcnt(5)
	v_mfma_f32_32x32x16_bf16 v[48:63], v[146:149], v[162:165], v[48:63]
	v_mfma_f32_32x32x16_bf16 v[32:47], v[150:153], v[162:165], v[32:47]
	v_mfma_f32_32x32x16_bf16 v[16:31], v[154:157], v[162:165], v[16:31]
	v_mfma_f32_32x32x16_bf16 v[0:15], v[158:161], v[162:165], v[0:15]
	s_setprio 0
	s_and_saveexec_b64 s[6:7], vcc
	s_cbranch_execz .LBB0_1687
	s_xor_b32 s13, s13, 0x10000
	s_add_i32 s13, s13, 0
	v_add_u32_e32 v121, s13, v106
	v_add_u32_e32 v148, s13, v105
	v_readfirstlane_b32 s14, v121
	v_lshl_add_u64 v[146:147], v[76:77], 0, s[4:5]
	s_mov_b32 m0, s14
	v_readfirstlane_b32 s14, v148
	v_add_u32_e32 v149, s13, v104
	global_load_lds_dwordx4 v[146:147], off
	v_lshl_add_u64 v[146:147], v[78:79], 0, s[4:5]
	s_mov_b32 m0, s14
	v_readfirstlane_b32 s14, v149
	v_add_u32_e32 v149, s13, v103
	global_load_lds_dwordx4 v[146:147], off
	v_lshl_add_u64 v[146:147], v[80:81], 0, s[4:5]
	s_mov_b32 m0, s14
	v_readfirstlane_b32 s13, v149
	v_add_u32_e32 v121, 0x8000, v121
	global_load_lds_dwordx4 v[146:147], off
	v_lshl_add_u64 v[146:147], v[82:83], 0, s[4:5]
	s_mov_b32 m0, s13
	v_readfirstlane_b32 s13, v121
	v_add_u32_e32 v121, 0x8000, v148
	global_load_lds_dwordx4 v[146:147], off
	v_lshl_add_u64 v[146:147], v[84:85], 0, s[4:5]
	s_mov_b32 m0, s13
	v_readfirstlane_b32 s13, v121
	global_load_lds_dwordx4 v[146:147], off
	v_lshl_add_u64 v[146:147], v[86:87], 0, s[4:5]
	s_mov_b32 m0, s13
	s_nop 0
	global_load_lds_dwordx4 v[146:147], off
.LBB0_1687:
	s_or_b64 exec, exec, s[6:7]
	v_add_u32_e32 v121, v120, v99
	ds_read_b128 v[146:149], v121
	ds_read_b128 v[150:153], v121 offset:4096
	ds_read_b128 v[154:157], v121 offset:8192
	ds_read_b128 v[158:161], v121 offset:12288
	v_add_u32_e32 v121, v119, v99
	ds_read_b128 v[162:165], v121 offset:32768
	s_setprio 1
	s_waitcnt lgkmcnt(5)
	v_mfma_f32_32x32x16_bf16 v[48:63], v[122:125], v[142:145], v[48:63]
	v_mfma_f32_32x32x16_bf16 v[32:47], v[130:133], v[142:145], v[32:47]
	v_mfma_f32_32x32x16_bf16 v[16:31], v[134:137], v[142:145], v[16:31]
	v_mfma_f32_32x32x16_bf16 v[0:15], v[138:141], v[142:145], v[0:15]
	s_waitcnt lgkmcnt(0)
	v_mfma_f32_32x32x16_bf16 v[48:63], v[146:149], v[162:165], v[48:63]
	v_mfma_f32_32x32x16_bf16 v[32:47], v[150:153], v[162:165], v[32:47]
	v_mfma_f32_32x32x16_bf16 v[16:31], v[154:157], v[162:165], v[16:31]
	v_mfma_f32_32x32x16_bf16 v[0:15], v[158:161], v[162:165], v[0:15]
	s_setprio 0
	s_xor_b32 s6, s9, 1
	s_waitcnt vmcnt(0)
	s_add_u32 s4, s4, 0x80
	s_addc_u32 s5, s5, 0
	s_cmpk_lg_i32 s4, 0x780
	s_waitcnt vmcnt(0)
	s_barrier
	s_cbranch_scc1 .LBB0_1683
	v_add_u32_e32 v70, s8, v117
	s_movk_i32 s4, 0x59
	v_cmp_lt_i32_e32 vcc, s4, v70
	s_mov_b32 s4, 0x2aaaaaab
	s_nop 0
	v_cndmask_b32_e32 v64, v70, v117, vcc
	v_mul_hi_i32 v65, v64, s4
	v_lshrrev_b32_e32 v66, 31, v65
	v_add_u32_e32 v68, v65, v66
	v_mul_lo_u32 v65, v68, 6
	v_sub_u32_e32 v64, v64, v65
	v_add_lshl_u32 v71, v64, v88, 8
	v_lshlrev_b32_e32 v64, 4, v118
	v_and_b32_e32 v128, 0x70, v64
	s_xor_b64 s[4:5], s[0:1], -1
	v_lshl_add_u64 v[66:67], s[42:43], 0, v[128:129]
	v_lshl_add_u64 v[64:65], s[44:45], 0, v[128:129]
	v_lshlrev_b32_e32 v72, 7, v68
	s_nor_b64 s[4:5], s[4:5], vcc
	s_and_saveexec_b64 s[14:15], s[4:5]
	s_xor_b64 s[4:5], exec, s[14:15]
	s_cbranch_execz .LBB0_1690
	s_lshl_b32 s7, s6, 16
	s_xor_b32 s13, s7, 0x10000
	v_add_u32_e32 v68, v71, v114
	s_add_i32 s13, s13, 0
	v_ashrrev_i32_e32 v69, 31, v68
	v_add_u32_e32 v73, s13, v106
	v_lshlrev_b64 v[68:69], 11, v[68:69]
	v_readfirstlane_b32 s14, v73
	v_add_u32_e32 v74, v113, v71
	v_lshl_add_u64 v[68:69], v[66:67], 0, v[68:69]
	s_mov_b32 m0, s14
	v_add_u32_e32 v80, s13, v105
	v_ashrrev_i32_e32 v75, 31, v74
	v_add_u32_e32 v76, v116, v71
	global_load_lds_dwordx4 v[68:69], off
	v_readfirstlane_b32 s14, v80
	v_add_u32_e32 v68, s13, v104
	v_lshlrev_b64 v[74:75], 11, v[74:75]
	v_ashrrev_i32_e32 v77, 31, v76
	v_add_u32_e32 v78, v115, v71
	s_mov_b32 m0, s14
	v_readfirstlane_b32 s14, v68
	v_add_u32_e32 v68, s13, v103
	v_lshlrev_b64 v[76:77], 11, v[76:77]
	v_ashrrev_i32_e32 v79, 31, v78
	v_lshl_add_u64 v[74:75], v[66:67], 0, v[74:75]
	v_readfirstlane_b32 s13, v68
	v_add_u32_e32 v68, v72, v114
	v_lshlrev_b64 v[78:79], 11, v[78:79]
	v_lshl_add_u64 v[76:77], v[66:67], 0, v[76:77]
	global_load_lds_dwordx4 v[74:75], off
	s_mov_b32 m0, s14
	v_ashrrev_i32_e32 v69, 31, v68
	v_add_u32_e32 v73, 0x8000, v73
	v_lshl_add_u64 v[78:79], v[66:67], 0, v[78:79]
	global_load_lds_dwordx4 v[76:77], off
	s_mov_b32 m0, s13
	v_lshlrev_b64 v[68:69], 11, v[68:69]
	v_readfirstlane_b32 s13, v73
	global_load_lds_dwordx4 v[78:79], off
	v_lshl_add_u64 v[68:69], v[64:65], 0, v[68:69]
	s_mov_b32 m0, s13
	v_add_u32_e32 v73, 0x8000, v80
	global_load_lds_dwordx4 v[68:69], off
	v_add_u32_e32 v68, v113, v72
	v_ashrrev_i32_e32 v69, 31, v68
	v_lshlrev_b64 v[68:69], 11, v[68:69]
	v_readfirstlane_b32 s13, v73
	v_lshl_add_u64 v[68:69], v[64:65], 0, v[68:69]
	s_mov_b32 m0, s13
	s_nop 0
	global_load_lds_dwordx4 v[68:69], off
